# P11 final-norm loop: gain vectors loaded once before the loop instead of after every store pair
# baseline (speedup 1.0000x reference)
.LBB0_1229:
	s_or_b64 exec, exec, s[2:3]
	s_waitcnt lgkmcnt(0)
	s_barrier
	v_readlane_b32 s3, v255, 0
	v_readfirstlane_b32 s2, v216
	s_ashr_i32 s2, s2, 6
	s_add_i32 s2, s2, s3
	s_cmp_lt_i32 s2, 0x10000
	s_cbranch_scc0 .LBB0_1238
	s_load_dwordx2 s[20:21], s[0:1], 0x90
	s_load_dwordx4 s[4:7], s[0:1], 0x80
	s_lshl_b32 s8, s42, 5
	v_and_b32_e32 v4, 63, v216
	v_mov_b32_e32 v37, 0
	s_waitcnt lgkmcnt(0)
	s_add_u32 s30, s20, 0x300000
	v_lshlrev_b32_e32 v36, 5, v4
	v_lshlrev_b32_e32 v0, 4, v4
	s_addc_u32 s31, s21, 0
	v_mov_b32_e32 v1, v37
	v_lshl_add_u64 v[42:43], s[4:5], 0, v[36:37]
	s_add_i32 s4, s2, s33
	v_lshl_add_u64 v[2:3], s[20:21], 0, v[0:1]
	s_mov_b64 s[10:11], 0x8000000
	s_ashr_i32 s5, s4, 31
	s_ashr_i32 s9, s8, 31
	s_ashr_i32 s3, s2, 31
	v_lshl_add_u64 v[38:39], v[2:3], 0, s[10:11]
	s_lshl_b64 s[10:11], s[4:5], 12
	s_lshl_b64 s[12:13], s[8:9], 12
	s_lshl_b64 s[4:5], s[2:3], 12
	s_add_u32 s14, s6, s4
	s_addc_u32 s15, s7, s5
	s_lshl_b64 s[4:5], s[2:3], 4
	s_add_u32 s4, s20, s4
	s_addc_u32 s5, s21, s5
	s_add_u32 s16, s4, 0x300000
	s_addc_u32 s17, s5, 0
	s_lshl_b64 s[18:19], s[8:9], 4
	s_lshl_b64 s[4:5], s[2:3], 11
	s_add_u32 s4, s20, s4
	v_lshlrev_b32_e32 v40, 3, v4
	s_addc_u32 s5, s21, s5
	v_lshrrev_b32_e32 v2, 2, v40
	v_lshl_add_u64 v[0:1], s[4:5], 0, v[0:1]
	s_mov_b64 s[4:5], 0x8000400
	v_lshlrev_b32_e32 v44, 1, v4
	v_or_b32_e32 v46, 0x80, v2
	v_lshl_add_u64 v[48:49], v[0:1], 0, s[4:5]
	s_lshl_b64 s[20:21], s[8:9], 11
	s_lshl_b32 s3, s42, 4
	s_mul_i32 s9, s42, 24
	v_mov_b32_e32 v41, 0x358637bd
	global_load_dwordx4 v[80:83], v[42:43], off
	global_load_dwordx4 v[84:87], v[42:43], off offset:16
	global_load_dwordx4 v[88:91], v[42:43], off offset:2048
	global_load_dwordx4 v[92:95], v[42:43], off offset:2064
	s_waitcnt vmcnt(0)
	s_branch .LBB0_1232

.LBB0_1232:
	global_load_dwordx4 v[50:53], v[48:49], off offset:-1024
	global_load_dwordx4 v[54:57], v37, s[16:17]
	s_add_i32 s27, s33, s2
	s_cmp_lt_i32 s27, 0x10000
	s_cselect_b32 s4, s27, s2
	s_ashr_i32 s5, s4, 31
	s_lshl_b64 s[6:7], s[4:5], 11
	s_lshl_b64 s[4:5], s[4:5], 4
	s_add_u32 s4, s30, s4
	s_addc_u32 s5, s31, s5
	s_add_i32 s26, s3, s2
	s_cmp_lt_i32 s26, 0x10000
	s_cselect_b64 s[28:29], -1, 0
	s_and_b64 s[22:23], s[28:29], exec
	s_cselect_b32 s22, s26, s2
	s_ashr_i32 s23, s22, 31
	s_lshl_b64 s[34:35], s[22:23], 11
	s_lshl_b64 s[22:23], s[22:23], 4
	s_add_u32 s36, s30, s22
	s_addc_u32 s37, s31, s23
	s_add_i32 s22, s9, s2
	s_cmp_lt_i32 s22, 0x10000
	s_cselect_b64 s[24:25], -1, 0
	s_and_b64 s[38:39], s[24:25], exec
	s_cselect_b32 s38, s22, s2
	s_ashr_i32 s39, s38, 31
	s_lshl_b64 s[40:41], s[38:39], 11
	s_lshl_b64 s[38:39], s[38:39], 4
	s_add_u32 s38, s30, s38
	s_addc_u32 s39, s31, s39
	v_lshl_add_u64 v[0:1], v[38:39], 0, s[6:7]
	global_load_dwordx4 v[4:7], v37, s[38:39]
	global_load_dwordx4 v[66:69], v[48:49], off
	global_load_dwordx4 v[28:31], v[0:1], off
	global_load_dwordx4 v[24:27], v[0:1], off offset:1024
	v_lshl_add_u64 v[0:1], v[38:39], 0, s[34:35]
	v_lshl_add_u64 v[72:73], v[38:39], 0, s[40:41]
	global_load_dwordx4 v[16:19], v[0:1], off
	global_load_dwordx4 v[12:15], v[0:1], off offset:1024
	global_load_dwordx4 v[32:35], v37, s[4:5]
	global_load_dwordx4 v[20:23], v37, s[36:37]
	global_load_dwordx4 v[8:11], v[72:73], off
	s_nop 0
	global_load_dwordx4 v[0:3], v[72:73], off offset:1024
	v_lshl_add_u64 v[70:71], s[14:15], 0, v[36:37]
	s_cmp_gt_i32 s27, 0xffff
	s_waitcnt vmcnt(11)
	v_lshlrev_b32_e32 v72, 16, v50
	s_waitcnt vmcnt(10)
	v_mov_b32_e32 v76, v55
	v_mov_b32_e32 v77, v56
	v_mov_b32_e32 v55, v57
	v_pk_add_f32 v[54:55], v[76:77], v[54:55]
	v_and_b32_e32 v73, 0xffff0000, v50
	v_add_f32_e32 v45, v54, v55
	v_fmamk_f32 v45, v45, 0x3a800000, v41
	v_rsq_f32_e32 v76, v45
	v_lshlrev_b32_e32 v50, 16, v51
	v_and_b32_e32 v51, 0xffff0000, v51
	v_lshlrev_b32_e32 v74, 16, v52
	v_and_b32_e32 v75, 0xffff0000, v52
	v_lshlrev_b32_e32 v52, 16, v53
	v_and_b32_e32 v53, 0xffff0000, v53
	v_pk_mul_f32 v[54:55], v[76:77], v[72:73] op_sel_hi:[0,1]
	v_pk_mul_f32 v[56:57], v[76:77], v[50:51] op_sel_hi:[0,1]
	v_pk_mul_f32 v[72:73], v[76:77], v[74:75] op_sel_hi:[0,1]
	v_pk_mul_f32 v[74:75], v[76:77], v[52:53] op_sel_hi:[0,1]
	v_pk_mul_f32 v[50:51], v[54:55], v[80:81]
	v_pk_mul_f32 v[52:53], v[56:57], v[82:83]
	v_pk_mul_f32 v[54:55], v[72:73], v[84:85]
	v_pk_mul_f32 v[56:57], v[74:75], v[86:87]
	global_store_dwordx4 v[70:71], v[50:53], off
	global_store_dwordx4 v[70:71], v[54:57], off offset:16
	v_lshlrev_b32_e32 v45, 2, v40
	s_waitcnt vmcnt(10)
	v_lshlrev_b32_e32 v58, 16, v66
	v_and_b32_e32 v59, 0xffff0000, v66
	v_lshlrev_b32_e32 v60, 16, v67
	v_and_b32_e32 v61, 0xffff0000, v67
	v_lshlrev_b32_e32 v62, 16, v68
	v_and_b32_e32 v63, 0xffff0000, v68
	v_lshlrev_b32_e32 v64, 16, v69
	v_and_b32_e32 v65, 0xffff0000, v69
	v_pk_mul_f32 v[58:59], v[76:77], v[58:59] op_sel_hi:[0,1]
	v_pk_mul_f32 v[60:61], v[76:77], v[60:61] op_sel_hi:[0,1]
	v_pk_mul_f32 v[62:63], v[76:77], v[62:63] op_sel_hi:[0,1]
	v_pk_mul_f32 v[64:65], v[76:77], v[64:65] op_sel_hi:[0,1]
	v_pk_mul_f32 v[50:51], v[58:59], v[88:89]
	v_pk_mul_f32 v[52:53], v[60:61], v[90:91]
	v_pk_mul_f32 v[54:55], v[62:63], v[92:93]
	v_pk_mul_f32 v[56:57], v[64:65], v[94:95]
	global_store_dwordx4 v[70:71], v[50:53], off offset:2048
	global_store_dwordx4 v[70:71], v[54:57], off offset:2064
	s_waitcnt vmcnt(4)
	s_cbranch_scc1 .LBB0_1235
	s_load_dwordx4 s[4:7], s[0:1], 0x80
	v_mov_b32_e32 v58, v33
	v_mov_b32_e32 v59, v34
	v_mov_b32_e32 v33, v35
	v_pk_add_f32 v[32:33], v[58:59], v[32:33]
	s_waitcnt lgkmcnt(0)
	v_add_f32_e32 v32, v32, v33
	v_fmamk_f32 v32, v32, 0x3a800000, v41
	v_rsq_f32_e32 v58, v32
	v_lshlrev_b32_e32 v34, 16, v28
	v_and_b32_e32 v35, 0xffff0000, v28
	v_lshlrev_b32_e32 v28, 16, v29
	v_and_b32_e32 v29, 0xffff0000, v29
	v_lshl_add_u64 v[32:33], s[6:7], 0, v[36:37]
	v_lshlrev_b32_e32 v60, 16, v30
	v_and_b32_e32 v61, 0xffff0000, v30
	v_lshlrev_b32_e32 v30, 16, v31
	v_and_b32_e32 v31, 0xffff0000, v31
	v_lshl_add_u64 v[62:63], v[32:33], 0, s[10:11]
	v_pk_mul_f32 v[32:33], v[58:59], v[34:35] op_sel_hi:[0,1]
	v_pk_mul_f32 v[34:35], v[58:59], v[28:29] op_sel_hi:[0,1]
	v_pk_mul_f32 v[60:61], v[58:59], v[60:61] op_sel_hi:[0,1]
	v_pk_mul_f32 v[64:65], v[58:59], v[30:31] op_sel_hi:[0,1]
	v_pk_mul_f32 v[28:29], v[32:33], v[80:81]
	v_pk_mul_f32 v[30:31], v[34:35], v[82:83]
	v_pk_mul_f32 v[32:33], v[60:61], v[84:85]
	v_pk_mul_f32 v[34:35], v[64:65], v[86:87]
	global_store_dwordx4 v[62:63], v[28:31], off
	global_store_dwordx4 v[62:63], v[32:35], off offset:16
	v_lshlrev_b32_e32 v50, 16, v24
	v_and_b32_e32 v51, 0xffff0000, v24
	v_lshlrev_b32_e32 v24, 16, v25
	v_and_b32_e32 v25, 0xffff0000, v25
	v_lshlrev_b32_e32 v52, 16, v26
	v_and_b32_e32 v53, 0xffff0000, v26
	v_lshlrev_b32_e32 v26, 16, v27
	v_and_b32_e32 v27, 0xffff0000, v27
	v_pk_mul_f32 v[50:51], v[58:59], v[50:51] op_sel_hi:[0,1]
	v_pk_mul_f32 v[54:55], v[58:59], v[24:25] op_sel_hi:[0,1]
	v_pk_mul_f32 v[52:53], v[58:59], v[52:53] op_sel_hi:[0,1]
	v_pk_mul_f32 v[56:57], v[58:59], v[26:27] op_sel_hi:[0,1]
	v_pk_mul_f32 v[24:25], v[50:51], v[88:89]
	v_pk_mul_f32 v[26:27], v[54:55], v[90:91]
	v_pk_mul_f32 v[28:29], v[52:53], v[92:93]
	v_pk_mul_f32 v[30:31], v[56:57], v[94:95]
	global_store_dwordx4 v[62:63], v[24:27], off offset:2048
	global_store_dwordx4 v[62:63], v[28:31], off offset:2064
	s_andn2_b64 vcc, exec, s[28:29]
	v_lshlrev_b32_e32 v25, 4, v44
	v_lshlrev_b32_e32 v24, 4, v46
	s_cbranch_vccz .LBB0_1236

.LBB0_1236:
	s_load_dwordx4 s[4:7], s[0:1], 0x80
	v_add_f32_e32 v34, v20, v21
	v_add_f32_e32 v35, v22, v23
	v_add_f32_e32 v34, v34, v35
	v_fmamk_f32 v34, v34, 0x3a800000, v41
	s_waitcnt lgkmcnt(0)
	v_rsq_f32_e32 v34, v34
	s_ashr_i32 s27, s26, 31
	v_lshlrev_b32_e32 v20, 16, v16
	v_and_b32_e32 v21, 0xffff0000, v16
	v_lshlrev_b32_e32 v16, 16, v17
	v_and_b32_e32 v17, 0xffff0000, v17
	s_lshl_b64 s[26:27], s[26:27], 12
	v_lshlrev_b32_e32 v22, 16, v18
	v_and_b32_e32 v23, 0xffff0000, v18
	v_lshlrev_b32_e32 v18, 16, v19
	v_and_b32_e32 v19, 0xffff0000, v19
	s_add_u32 s6, s6, s26
	v_pk_mul_f32 v[20:21], v[34:35], v[20:21] op_sel_hi:[0,1]
	v_pk_mul_f32 v[50:51], v[34:35], v[16:17] op_sel_hi:[0,1]
	s_addc_u32 s7, s7, s27
	v_pk_mul_f32 v[22:23], v[34:35], v[22:23] op_sel_hi:[0,1]
	v_pk_mul_f32 v[52:53], v[34:35], v[18:19] op_sel_hi:[0,1]
	v_pk_mul_f32 v[16:17], v[20:21], v[80:81]
	v_pk_mul_f32 v[18:19], v[50:51], v[82:83]
	v_pk_mul_f32 v[20:21], v[22:23], v[84:85]
	v_pk_mul_f32 v[22:23], v[52:53], v[86:87]
	global_store_dwordx4 v25, v[16:19], s[6:7]
	global_store_dwordx4 v25, v[20:23], s[6:7] offset:16
	v_lshlrev_b32_e32 v26, 16, v12
	v_and_b32_e32 v27, 0xffff0000, v12
	v_lshlrev_b32_e32 v12, 16, v13
	v_and_b32_e32 v13, 0xffff0000, v13
	v_lshlrev_b32_e32 v28, 16, v14
	v_and_b32_e32 v29, 0xffff0000, v14
	v_lshlrev_b32_e32 v14, 16, v15
	v_and_b32_e32 v15, 0xffff0000, v15
	v_pk_mul_f32 v[26:27], v[34:35], v[26:27] op_sel_hi:[0,1]
	v_pk_mul_f32 v[30:31], v[34:35], v[12:13] op_sel_hi:[0,1]
	v_pk_mul_f32 v[28:29], v[34:35], v[28:29] op_sel_hi:[0,1]
	v_pk_mul_f32 v[32:33], v[34:35], v[14:15] op_sel_hi:[0,1]
	v_pk_mul_f32 v[12:13], v[26:27], v[88:89]
	v_pk_mul_f32 v[14:15], v[30:31], v[90:91]
	v_pk_mul_f32 v[16:17], v[28:29], v[92:93]
	v_pk_mul_f32 v[18:19], v[32:33], v[94:95]
	global_store_dwordx4 v24, v[12:15], s[6:7]
	global_store_dwordx4 v24, v[16:19], s[6:7] offset:16
	s_andn2_b64 vcc, exec, s[24:25]
	s_cbranch_vccnz .LBB0_1231
.LBB0_1237:
	s_load_dwordx4 s[4:7], s[0:1], 0x80
	v_add_f32_e32 v20, v4, v5
	v_add_f32_e32 v21, v6, v7
	v_add_f32_e32 v20, v20, v21
	v_fmamk_f32 v20, v20, 0x3a800000, v41
	s_waitcnt lgkmcnt(0)
	v_rsq_f32_e32 v20, v20
	s_ashr_i32 s23, s22, 31
	v_lshlrev_b32_e32 v4, 16, v8
	v_and_b32_e32 v5, 0xffff0000, v8
	v_lshlrev_b32_e32 v6, 16, v9
	v_and_b32_e32 v7, 0xffff0000, v9
	s_lshl_b64 s[22:23], s[22:23], 12
	v_lshlrev_b32_e32 v8, 16, v10
	v_and_b32_e32 v9, 0xffff0000, v10
	v_lshlrev_b32_e32 v10, 16, v11
	v_and_b32_e32 v11, 0xffff0000, v11
	s_add_u32 s6, s6, s22
	v_pk_mul_f32 v[4:5], v[20:21], v[4:5] op_sel_hi:[0,1]
	v_pk_mul_f32 v[6:7], v[20:21], v[6:7] op_sel_hi:[0,1]
	s_addc_u32 s7, s7, s23
	v_pk_mul_f32 v[8:9], v[20:21], v[8:9] op_sel_hi:[0,1]
	v_pk_mul_f32 v[10:11], v[20:21], v[10:11] op_sel_hi:[0,1]
	v_pk_mul_f32 v[4:5], v[4:5], v[80:81]
	v_pk_mul_f32 v[6:7], v[6:7], v[82:83]
	v_pk_mul_f32 v[8:9], v[8:9], v[84:85]
	v_pk_mul_f32 v[10:11], v[10:11], v[86:87]
	global_store_dwordx4 v25, v[4:7], s[6:7]
	global_store_dwordx4 v25, v[8:11], s[6:7] offset:16
	v_lshlrev_b32_e32 v12, 16, v0
	v_and_b32_e32 v13, 0xffff0000, v0
	v_lshlrev_b32_e32 v0, 16, v1
	v_and_b32_e32 v1, 0xffff0000, v1
	v_lshlrev_b32_e32 v14, 16, v2
	v_and_b32_e32 v15, 0xffff0000, v2
	v_lshlrev_b32_e32 v2, 16, v3
	v_and_b32_e32 v3, 0xffff0000, v3
	v_pk_mul_f32 v[12:13], v[20:21], v[12:13] op_sel_hi:[0,1]
	v_pk_mul_f32 v[16:17], v[20:21], v[0:1] op_sel_hi:[0,1]
	v_pk_mul_f32 v[14:15], v[20:21], v[14:15] op_sel_hi:[0,1]
	v_pk_mul_f32 v[18:19], v[20:21], v[2:3] op_sel_hi:[0,1]
	v_pk_mul_f32 v[0:1], v[12:13], v[88:89]
	v_pk_mul_f32 v[2:3], v[16:17], v[90:91]
	v_pk_mul_f32 v[4:5], v[14:15], v[92:93]
	v_pk_mul_f32 v[6:7], v[18:19], v[94:95]
	global_store_dwordx4 v24, v[0:3], s[6:7]
	global_store_dwordx4 v24, v[4:7], s[6:7] offset:16
	s_branch .LBB0_1231
